# phase-2 worker blocks 288 instead of 248
# speedup vs baseline: 1.0189x; 1.0189x over previous
; __device__ __forceinline__ int ltid() { int t = threadIdx.x; asm volatile("" : "+v"(t)); return t; }
; template <bool SIGNAL>
; __device__ __forceinline__ void phase2(const Params& p, unsigned char* smem, const int lo, const int hi, const int worker, const int nworkers) {
;   u16* DX = (u16*)(p.ws + OFF_DX); const u16* HALO = (const u16*)(p.ws + OFF_HALO);
;   const float* BETA = (const float*)(p.ws + OFF_BETA); const float* GG = (const float*)(p.ws + OFF_G);
;   u16* TA = (u16*)(p.ws + OFF_EXTRA);
;   float* sin = (float*)smem;
;   u16* sq = (u16*)(smem + 34304);
;   u16* sk = sq + 64 * 136;
;   u16* svT = sq;
;   float* sgc = (float*)(smem + 34304 + 34816);
;   float* sbeta = sgc + 64;
;   float* sM = (float*)smem;
;   const int tid = ltid(), lane = tid & 63, wave = tid >> 6;
;   const int l31 = lane & 31, hf = lane >> 5;
;   for (int idx2 = lo + worker; idx2 < hi; idx2 += nworkers) {
;     const int bh = idx2 & 15, c = idx2 >> 4; const int it = bh * NCH + c; const int h = bh & 7;
; __device__ __forceinline__ void phase3(const Params& p, unsigned char* smem, unsigned* bar) {
;     ...
;     phase2<true>(p, smem, P2_SPLIT * 16, NCH * 16, blockIdx.x - 16, gridDim.x - 16);
.LBB0_250:
	s_or_b64 exec, exec, s[4:5]
	v_mov_b32_e32 v220, v218
	v_writelane_b32 v247, s12, 0
	s_cmp_gt_u32 s89, 15
	s_mov_b64 s[4:5], -1
	v_writelane_b32 v247, s13, 1
	s_barrier
	s_cbranch_scc0 .LBB0_311
	s_add_i32 s84, s89, -16
	v_mov_b32_e32 v32, v218
	s_add_i32 s2, s3, -16
	s_min_u32 s2, s2, 0x120
	s_cmp_ge_i32 s84, s2
	v_writelane_b32 v247, s73, 2
	s_cbranch_scc1 .LBB0_310
	s_load_dwordx2 s[6:7], s[0:1], 0x90
	v_lshlrev_b32_e32 v7, 3, v32
	v_and_b32_e32 v0, 0x78, v7
	v_mov_b32_e32 v35, 0
	v_lshlrev_b32_e32 v34, 1, v0
	s_waitcnt lgkmcnt(0)
	s_add_u32 s85, s6, 0x6090000
	s_addc_u32 s86, s7, 0
	s_add_u32 s2, s6, 0xee1d000
	v_writelane_b32 v247, s2, 3
	s_addc_u32 s2, s7, 0
	v_writelane_b32 v247, s2, 4
	s_add_u32 s2, s6, 0xee9e000
	v_writelane_b32 v247, s2, 5
	s_addc_u32 s2, s7, 0
	v_writelane_b32 v247, s2, 6
	s_add_u32 s2, s6, 0xc5d9000
	v_writelane_b32 v247, s2, 7
	s_addc_u32 s2, s7, 0
	v_lshl_add_u64 v[4:5], s[6:7], 0, v[34:35]
	s_mov_b64 s[12:13], 0xc150000
	v_writelane_b32 v247, s2, 8
	v_lshl_add_u64 v[36:37], v[4:5], 0, s[12:13]
	v_cmp_gt_i32_e64 s[12:13], 64, v32
	v_and_b32_e32 v39, 63, v32
	v_ashrrev_i32_e32 v2, 6, v32
	v_writelane_b32 v247, s12, 9
	v_and_b32_e32 v1, 31, v32
	v_and_b32_e32 v38, 56, v7
	v_writelane_b32 v247, s13, 10
	v_cmp_eq_u32_e64 s[12:13], 0, v32
	v_lshlrev_b32_e32 v7, 5, v2
	v_and_or_b32 v1, v7, 32, v1
	v_writelane_b32 v247, s12, 11
	s_movk_i32 s11, 0x110
	v_ashrrev_i32_e32 v13, 2, v32
	v_writelane_b32 v247, s13, 12
	v_cmp_eq_u32_e64 s[12:13], 0, v39
	s_movk_i32 s8, 0xffe0
	v_bfe_u32 v6, v32, 5, 1
	v_writelane_b32 v247, s12, 13
	v_mad_u32_u24 v11, v1, s11, 16
	v_and_b32_e32 v14, 0xffffffe0, v13
	v_writelane_b32 v247, s13, 14
	v_cmp_gt_u32_e64 s[12:13], 2, v39
	v_bfi_b32 v13, s8, v13, v32
	s_movk_i32 s8, 0xfef4
	v_writelane_b32 v247, s12, 15
	v_mul_u32_u24_e32 v4, 0x118, v39
	v_lshlrev_b32_e32 v5, 3, v39
	v_writelane_b32 v247, s13, 16
	v_cmp_gt_u32_e64 s[12:13], 4, v39
	v_lshl_add_u32 v10, v38, 1, 16
	v_lshlrev_b32_e32 v12, 4, v6
	v_writelane_b32 v247, s12, 17
	v_lshl_or_b32 v20, v6, 2, v14
	v_mad_i32_i24 v6, v1, s8, v11
	v_writelane_b32 v247, s13, 18
	v_cmp_gt_u32_e64 s[12:13], 8, v39
	s_movk_i32 s8, 0x10e
	v_add3_u32 v9, 16, v5, v4
	v_writelane_b32 v247, s12, 19
	v_add_u32_e32 v108, v11, v12
	v_lshlrev_b32_e32 v11, 4, v39
	v_writelane_b32 v247, s13, 20
	v_cmp_gt_u32_e64 s[12:13], 16, v39
	v_mad_u32_u24 v21, v38, s8, v10
	s_movk_i32 s8, 0x42f
	v_writelane_b32 v247, s12, 21
	s_add_i32 s9, 16, 0x10e00
	s_add_i32 s10, 16, 0x10f00
	v_writelane_b32 v247, s13, 22
	v_cmp_gt_u32_e64 s[12:13], 32, v39
	v_sub_u32_e32 v111, v9, v11
	v_lshlrev_b32_e32 v9, 2, v32
	v_writelane_b32 v247, s12, 23
	v_add_u32_e32 v112, s9, v9
	v_add_u32_e32 v113, s10, v9
	v_writelane_b32 v247, s13, 24
	v_cmp_lt_i32_e64 s[12:13], s8, v32
	v_ashrrev_i32_e32 v9, 4, v32
	s_movk_i32 s8, 0x32f
	v_writelane_b32 v247, s12, 25
	v_cmp_gt_i32_e64 s[26:27], 3, v9
	v_lshlrev_b32_e32 v42, 7, v9
	v_writelane_b32 v247, s13, 26
	v_cmp_gt_i32_e64 s[12:13], 51, v9
	v_add_u32_e32 v9, 0x100, v32
	v_ashrrev_i32_e32 v11, 4, v9
	v_writelane_b32 v247, s12, 27
	v_mul_lo_u32 v13, v13, s11
	v_cmp_gt_i32_e64 s[34:35], 3, v11
	v_writelane_b32 v247, s13, 28
	v_cmp_lt_i32_e64 s[12:13], s8, v32
	s_movk_i32 s8, 0x22f
	v_lshlrev_b32_e32 v46, 7, v11
	v_writelane_b32 v247, s12, 29
	v_add3_u32 v109, 16, v13, v12
	v_lshl_add_u32 v8, v0, 2, 16
	v_writelane_b32 v247, s13, 30
	v_cmp_gt_i32_e64 s[12:13], 51, v11
	v_add_u32_e32 v11, 0x200, v32
	v_ashrrev_i32_e32 v12, 4, v11
	v_writelane_b32 v247, s12, 31
	v_cmp_gt_i32_e64 s[40:41], 3, v12
	v_lshlrev_b32_e32 v50, 7, v12
	v_writelane_b32 v247, s13, 32
	v_cmp_lt_i32_e64 s[12:13], s8, v32
	s_movk_i32 s8, 0x12f
	v_ashrrev_i32_e32 v22, 3, v32
	v_writelane_b32 v247, s12, 33
	v_ashrrev_i32_e32 v23, 3, v9
	v_lshlrev_b32_e32 v62, 6, v22
	v_writelane_b32 v247, s13, 34
	v_cmp_gt_i32_e64 s[12:13], 51, v12
	v_add_u32_e32 v12, 0x300, v32
	v_ashrrev_i32_e32 v13, 4, v12
	v_writelane_b32 v247, s12, 35
	v_cmp_gt_i32_e64 s[46:47], 3, v13
	v_lshlrev_b32_e32 v54, 7, v13
	v_writelane_b32 v247, s13, 36
	v_cmp_lt_i32_e64 s[12:13], s8, v32
	s_movk_i32 s8, 0x430
	v_cmp_gt_i32_e64 s[54:55], s8, v32
	v_writelane_b32 v247, s12, 37
	s_movk_i32 s8, 0x330
	v_cmp_gt_i32_e64 s[56:57], s8, v32
	v_writelane_b32 v247, s13, 38
	v_cmp_gt_i32_e64 s[12:13], 51, v13
	v_add_u32_e32 v13, 0x400, v32
	v_ashrrev_i32_e32 v14, 4, v13
	v_writelane_b32 v247, s12, 39
	v_cmp_gt_i32_e64 s[52:53], 3, v14
	v_lshlrev_b32_e32 v58, 7, v14
	v_writelane_b32 v247, s13, 40
	v_cmp_lt_i32_e64 s[12:13], 47, v32
	s_movk_i32 s8, 0x230
	v_lshlrev_b32_e32 v13, 5, v13
	v_writelane_b32 v247, s12, 41
	v_cmp_gt_i32_e64 s[58:59], s8, v32
	s_movk_i32 s8, 0x130
	v_writelane_b32 v247, s13, 42
	v_cmp_gt_i32_e64 s[12:13], 51, v14
	v_lshlrev_b32_e32 v14, 5, v32
	v_and_b32_e32 v14, 0xfffffe00, v14
	v_add_u32_e32 v114, v8, v14
	v_lshlrev_b32_e32 v14, 5, v9
	v_and_b32_e32 v14, 0xfffffe00, v14
	v_add_u32_e32 v115, v8, v14
	v_lshlrev_b32_e32 v14, 5, v11
	v_and_b32_e32 v14, 0xfffffe00, v14
	v_writelane_b32 v247, s12, 43
	v_add_u32_e32 v116, v8, v14
	v_lshlrev_b32_e32 v14, 5, v12
	v_writelane_b32 v247, s13, 44
	v_and_b32_e32 v14, 0xfffffe00, v14
	v_and_b32_e32 v13, 0xfffffe00, v13
	s_movk_i32 s12, 0x90
	v_cmp_gt_i32_e64 s[60:61], s8, v32
	v_add_u32_e32 v117, v8, v14
	v_add_u32_e32 v118, v8, v13
	v_mul_lo_u32 v8, v22, s12
	s_mov_b32 s8, 0x8600
	v_add3_u32 v119, v10, v8, s8
	v_mul_lo_u32 v8, v23, s12
	v_add3_u32 v120, v10, v8, s8
	v_ashrrev_i32_e32 v8, 3, v11
	v_mul_lo_u32 v9, v8, s12
	s_waitcnt vmcnt(6)
; __device__ __forceinline__ u16 f2bf(float f) { return (u16)(cvtpk(f, 0.f) & 0xffffu); }
; template <bool SIGNAL>
; __device__ __forceinline__ void phase2(const Params& p, unsigned char* smem, const int lo, const int hi, const int worker, const int nworkers) {
;     ...
;     u16* Tg = TA + (size_t)it * 8704; u16* Ag = Tg + 4096; float* SCg = (float*)(Tg + 8192);
;     {
;       const int j = 32 * tj + l31; const float gcj = sgc[j];
; #pragma unroll
;       for (int r = 0; r < 16; ++r) {
;         const int i = 32 * ti + 8 * (r >> 2) + 4 * hf + (r & 3);
;         const float gci = sgc[i]; const float bi = sbeta[i];
;         const float dec = __expf(gci - gcj);
;         sM[i * 68 + j] = (j < i) ? bi * kk[r] * dec : 0.f;
;         Ag[i * 64 + j] = f2bf((j <= i) ? qk[r] * dec : 0.f);
;       }
;     }
	v_lshlrev_b32_e32 v66, 6, v8
	v_ashrrev_i32_e32 v8, 3, v12
	v_add3_u32 v121, v10, v9, s8
	v_mul_lo_u32 v9, v8, s12
	v_cmp_lt_i32_e64 s[12:13], v1, v20
	v_add3_u32 v122, v10, v9, s8
	v_or_b32_e32 v9, 1, v20
	v_writelane_b32 v247, s12, 45
	v_lshlrev_b32_e32 v10, 2, v9
	s_waitcnt vmcnt(5)
	v_lshl_or_b32 v72, v9, 6, v1
	v_writelane_b32 v247, s13, 46
	v_cmp_gt_i32_e64 s[12:13], v1, v9
	v_or_b32_e32 v9, 2, v20
	v_add_u32_e32 v125, s9, v10
	v_writelane_b32 v247, s12, 47
	v_add_u32_e32 v126, s10, v10
	v_lshlrev_b32_e32 v10, 2, v9
	v_writelane_b32 v247, s13, 48
	v_cmp_lt_i32_e64 s[12:13], v1, v9
	v_lshl_or_b32 v74, v9, 6, v1
	v_add_u32_e32 v127, s9, v10
	v_writelane_b32 v247, s12, 49
	v_add_u32_e32 v128, s10, v10
	v_lshlrev_b32_e32 v68, 6, v8
	v_writelane_b32 v247, s13, 50
	v_cmp_gt_i32_e64 s[12:13], v1, v9
	v_or_b32_e32 v9, 3, v20
	v_lshlrev_b32_e32 v10, 2, v9
	v_writelane_b32 v247, s12, 51
	s_waitcnt vmcnt(3)
	v_lshl_or_b32 v76, v9, 6, v1
	v_add_u32_e32 v129, s9, v10
	v_writelane_b32 v247, s13, 52
	v_cmp_lt_i32_e64 s[12:13], v1, v9
	v_add_u32_e32 v130, s10, v10
	v_lshlrev_b32_e32 v8, 2, v20
	v_writelane_b32 v247, s12, 53
	v_add_u32_e32 v123, s9, v8
	v_add_u32_e32 v124, s10, v8
	v_writelane_b32 v247, s13, 54
	v_cmp_gt_i32_e64 s[12:13], v1, v9
	v_or_b32_e32 v9, 8, v20
	v_lshlrev_b32_e32 v10, 2, v9
	v_add_u32_e32 v131, s9, v10
	v_add_u32_e32 v132, s10, v10
	v_or_b32_e32 v10, 9, v20
	v_lshlrev_b32_e32 v11, 2, v10
	v_add_u32_e32 v133, s9, v11
	v_add_u32_e32 v134, s10, v11
	v_or_b32_e32 v11, 10, v20
	v_lshlrev_b32_e32 v12, 2, v11
	v_add_u32_e32 v135, s9, v12
	v_add_u32_e32 v136, s10, v12
	v_or_b32_e32 v12, 11, v20
	v_lshlrev_b32_e32 v13, 2, v12
	v_add_u32_e32 v137, s9, v13
	v_add_u32_e32 v138, s10, v13
	v_or_b32_e32 v13, 16, v20
	v_lshlrev_b32_e32 v14, 2, v13
	v_add_u32_e32 v139, s9, v14
	v_add_u32_e32 v140, s10, v14
	v_or_b32_e32 v14, 17, v20
	v_lshlrev_b32_e32 v15, 2, v14
	v_add_u32_e32 v141, s9, v15
	v_add_u32_e32 v142, s10, v15
	v_or_b32_e32 v15, 18, v20
	v_lshlrev_b32_e32 v16, 2, v15
	v_add_u32_e32 v143, s9, v16
	v_add_u32_e32 v144, s10, v16
	v_or_b32_e32 v16, 19, v20
	v_lshlrev_b32_e32 v17, 2, v16
	v_add_u32_e32 v145, s9, v17
	v_add_u32_e32 v146, s10, v17
	v_or_b32_e32 v17, 24, v20
	v_lshlrev_b32_e32 v18, 2, v17
	v_add_u32_e32 v147, s9, v18
	v_add_u32_e32 v148, s10, v18
	v_or_b32_e32 v18, 25, v20
	v_lshlrev_b32_e32 v19, 2, v18
	v_writelane_b32 v247, s12, 55
	v_add_u32_e32 v149, s9, v19
	v_add_u32_e32 v150, s10, v19
	v_or_b32_e32 v19, 26, v20
	v_mul_lo_u32 v8, v20, s11
	v_cmp_gt_i32_e64 s[66:67], v1, v20
	v_lshl_or_b32 v70, v20, 6, v1
	v_writelane_b32 v247, s13, 56
	v_cmp_lt_i32_e64 s[12:13], v1, v9
	v_lshlrev_b32_e32 v24, 2, v19
	v_or_b32_e32 v20, 27, v20
	v_lshl_add_u32 v155, v22, 2, v21
	v_lshlrev_b32_e32 v22, 11, v2
	v_lshlrev_b32_e32 v3, 2, v39
	s_movk_i32 s2, 0x118
	v_lshlrev_b32_e32 v64, 6, v23
	v_writelane_b32 v247, s12, 57
	v_add_u32_e32 v151, s9, v24
	v_add_u32_e32 v152, s10, v24
	v_lshlrev_b32_e32 v24, 2, v20
	v_lshl_add_u32 v156, v23, 2, v21
	v_ashrrev_i32_e32 v23, 31, v22
	v_add_u32_e32 v104, s9, v3
	v_lshl_add_u32 v110, v1, 2, s9
	v_writelane_b32 v247, s13, 58
	v_add_u32_e32 v153, s9, v24
	s_add_i32 s9, s3, -16
	s_min_u32 s9, s9, 0x120
	v_mad_u32_u24 v7, v39, s2, v7
	s_movk_i32 s2, 0x1100
	v_lshlrev_b64 v[22:23], 1, v[22:23]
	v_writelane_b32 v247, s9, 59
	s_add_u32 s9, s6, 0xf223840
	v_add3_u32 v157, v7, v5, s8
	v_mul_lo_u32 v7, v2, s2
	v_or_b32_e32 v22, v22, v3
	v_cmp_gt_u32_e32 vcc, 48, v39
	v_add_u32_e32 v105, s10, v3
	v_lshlrev_b32_e32 v107, 4, v2
	v_writelane_b32 v247, s9, 60
	s_addc_u32 s9, s7, 0
	v_or_b32_e32 v158, v7, v3
	v_lshl_or_b32 v160, v2, 13, v5
	v_lshl_add_u64 v[2:3], s[6:7], 0, v[22:23]
	s_mov_b64 s[6:7], 0x6090200
	v_writelane_b32 v247, s9, 61
	v_lshl_add_u64 v[102:103], v[2:3], 0, s[6:7]
	s_xor_b64 s[6:7], vcc, -1
	v_writelane_b32 v247, s6, 62
	s_add_i32 s2, 16, 0x10efc
	v_sub_u32_e32 v2, v4, v5
	v_writelane_b32 v247, s7, 63
	v_writelane_b32 v246, s2, 0
	v_cmp_gt_i32_e64 s[6:7], v1, v9
	v_lshl_or_b32 v78, v9, 6, v1
	v_lshl_or_b32 v80, v10, 6, v1
	v_writelane_b32 v246, s6, 1
	v_lshl_or_b32 v82, v11, 6, v1
	s_waitcnt vmcnt(2)
; __device__ __forceinline__ u16 f2bf(float f) { return (u16)(cvtpk(f, 0.f) & 0xffffu); }
; template <bool SIGNAL>
; __device__ __forceinline__ void phase2(const Params& p, unsigned char* smem, const int lo, const int hi, const int worker, const int nworkers) {
;     ...
;       const int j = 32 * tj + l31; const float gcj = sgc[j];
; #pragma unroll
;       for (int r = 0; r < 16; ++r) {
;         const int i = 32 * ti + 8 * (r >> 2) + 4 * hf + (r & 3);
;         const float gci = sgc[i]; const float bi = sbeta[i];
;         const float dec = __expf(gci - gcj);
;         sM[i * 68 + j] = (j < i) ? bi * kk[r] * dec : 0.f;
;         Ag[i * 64 + j] = f2bf((j <= i) ? qk[r] * dec : 0.f);
;       }
;     }
	v_lshl_or_b32 v84, v12, 6, v1
	v_writelane_b32 v246, s7, 2
	v_cmp_lt_i32_e64 s[6:7], v1, v10
	v_lshl_or_b32 v86, v13, 6, v1
	s_waitcnt vmcnt(1)
	v_lshl_or_b32 v88, v14, 6, v1
	v_writelane_b32 v246, s6, 3
	v_lshl_or_b32 v90, v15, 6, v1
	s_waitcnt vmcnt(0)
	v_lshl_or_b32 v92, v16, 6, v1
	v_writelane_b32 v246, s7, 4
	v_cmp_gt_i32_e64 s[6:7], v1, v10
	v_lshl_or_b32 v94, v17, 6, v1
	v_lshl_or_b32 v96, v18, 6, v1
	v_writelane_b32 v246, s6, 5
	v_lshl_or_b32 v98, v19, 6, v1
	v_lshl_or_b32 v100, v20, 6, v1
	v_writelane_b32 v246, s7, 6
	v_cmp_lt_i32_e64 s[6:7], v1, v11
	v_add_u32_e32 v2, 16, v2
	v_cmp_gt_u32_e64 s[4:5], 64, v32
	v_writelane_b32 v246, s6, 7
	v_mov_b32_e32 v33, v35
	v_lshlrev_b32_e32 v106, 1, v39
	v_writelane_b32 v246, s7, 8
	v_cmp_gt_i32_e64 s[6:7], v1, v11
	v_ashrrev_i32_e32 v41, 31, v32
	v_mov_b32_e32 v40, v32
	v_writelane_b32 v246, s6, 9
	v_add_u32_e32 v44, 0xfffffe80, v42
	v_mov_b32_e32 v45, v35
	v_writelane_b32 v246, s7, 10
	v_cmp_lt_i32_e64 s[6:7], v1, v12
	v_ashrrev_i32_e32 v43, 31, v42
	v_add_u32_e32 v48, 0xfffffe80, v46
	v_writelane_b32 v246, s6, 11
	v_mov_b32_e32 v49, v35
	v_ashrrev_i32_e32 v47, 31, v46
	v_writelane_b32 v246, s7, 12
	v_cmp_gt_i32_e64 s[6:7], v1, v12
	v_add_u32_e32 v52, 0xfffffe80, v50
	v_mov_b32_e32 v53, v35
	v_writelane_b32 v246, s6, 13
	v_ashrrev_i32_e32 v51, 31, v50
	v_add_u32_e32 v56, 0xfffffe80, v54
	v_writelane_b32 v246, s7, 14
	v_cmp_lt_i32_e64 s[6:7], v1, v13
	v_mov_b32_e32 v57, v35
	v_ashrrev_i32_e32 v55, 31, v54
	v_writelane_b32 v246, s6, 15
	v_add_u32_e32 v60, 0xfffffe80, v58
	v_mov_b32_e32 v61, v35
	v_writelane_b32 v246, s7, 16
	v_cmp_gt_i32_e64 s[6:7], v1, v13
	v_ashrrev_i32_e32 v59, 31, v58
	v_cmp_gt_i32_e64 s[62:63], 48, v32
	v_writelane_b32 v246, s6, 17
	v_ashrrev_i32_e32 v63, 31, v62
	v_ashrrev_i32_e32 v65, 31, v64
	v_writelane_b32 v246, s7, 18
	v_cmp_lt_i32_e64 s[6:7], v1, v14
	v_ashrrev_i32_e32 v67, 31, v66
	v_ashrrev_i32_e32 v69, 31, v68
	v_writelane_b32 v246, s6, 19
	v_ashrrev_i32_e32 v71, 31, v70
	v_ashrrev_i32_e32 v73, 31, v72
	v_writelane_b32 v246, s7, 20
	v_cmp_gt_i32_e64 s[6:7], v1, v14
	v_ashrrev_i32_e32 v75, 31, v74
	v_ashrrev_i32_e32 v77, 31, v76
	v_writelane_b32 v246, s6, 21
	v_ashrrev_i32_e32 v79, 31, v78
	v_ashrrev_i32_e32 v81, 31, v80
	v_ashrrev_i32_e32 v83, 31, v82
	v_ashrrev_i32_e32 v85, 31, v84
	v_ashrrev_i32_e32 v87, 31, v86
	v_ashrrev_i32_e32 v89, 31, v88
	v_ashrrev_i32_e32 v91, 31, v90
	v_ashrrev_i32_e32 v93, 31, v92
	v_ashrrev_i32_e32 v95, 31, v94
	v_ashrrev_i32_e32 v97, 31, v96
	v_ashrrev_i32_e32 v99, 31, v98
	v_add_u32_e32 v154, s10, v24
	v_ashrrev_i32_e32 v101, 31, v100
	v_and_b32_e32 v159, 0xffffffc0, v32
	v_add_u32_e32 v161, 0x8600, v2
	v_lshlrev_b32_e32 v34, 1, v0
	s_add_i32 s87, 16, 0xca00
	s_mov_b32 s88, 0x800000
	v_add_u32_e32 v162, v6, v8
	v_mbcnt_hi_u32_b32 v163, -1, v219
	v_mov_b32_e32 v164, 0x300
	v_mov_b32_e32 v165, 0x3db504f3
	s_mov_b32 s2, s89
	v_writelane_b32 v246, s7, 22
	v_cmp_lt_i32_e64 s[10:11], v1, v15
	v_cmp_gt_i32_e64 s[12:13], v1, v15
	v_cmp_lt_i32_e64 s[14:15], v1, v16
	v_cmp_gt_i32_e64 s[16:17], v1, v16
	v_cmp_lt_i32_e64 s[18:19], v1, v17
	v_cmp_gt_i32_e64 s[20:21], v1, v17
	v_cmp_lt_i32_e64 s[6:7], v1, v18
	v_cmp_gt_i32_e64 s[8:9], v1, v18
	v_cmp_lt_i32_e64 s[22:23], v1, v19
	v_cmp_gt_i32_e64 s[24:25], v1, v19
	v_cmp_lt_i32_e64 s[28:29], v1, v20
	v_cmp_gt_i32_e64 s[30:31], v1, v20
	s_mov_b32 s64, 0x358637bd
	s_branch .LBB0_254
